# previous + non-temporal stores for the final y output in the GEMM4 epilogue
# baseline (speedup 1.0000x reference)
; #define PG8_STAGE(bufoff, gbase, voff) do { _Pragma("unroll") for (int _i = 0; _i < 2; ++_i) \
;         __builtin_amdgcn_global_load_lds((const unsigned*)((const char*)(gbase) + (voff)[_i]), (LAS unsigned*)(lds + (bufoff) + ldsw + _i * 8192), 16, 0, 0); } while (0)
; #define PG8_LDA(dst, b, h) do { _Pragma("unroll") for (int m = 0; m < 4; ++m) _Pragma("unroll") for (int k = 0; k < 2; ++k) dst[m][k] = *(const LAS bf16x8*)(lds + PG8_SA(b, h) + aoff + m * 2048 + k * 1024); } while (0)
; #define PG8_LDB(dst, b, h) do { _Pragma("unroll") for (int n = 0; n < 2; ++n) _Pragma("unroll") for (int k = 0; k < 2; ++k) dst[n][k] = *(const LAS bf16x8*)(lds + PG8_SB(b, h) + boff + n * 2048 + k * 1024); } while (0)
; #define PG8_MMA(ai, bj, At, Bt) do { __builtin_amdgcn_s_setprio(1); _Pragma("unroll") for (int m = 0; m < 4; ++m) _Pragma("unroll") for (int n = 0; n < 2; ++n) _Pragma("unroll") for (int k = 0; k < 2; ++k) \
;         acc[ai][bj][m][n] = __builtin_amdgcn_mfma_f32_16x16x32_bf16(Bt[n][k], At[m][k], acc[ai][bj][m][n], 0, 0, 0); __builtin_amdgcn_s_setprio(0); } while (0)
; template <class Epi>
; __device__ __forceinline__ void gemm_phase(LAS unsigned char* lds, const Gemm g, const StaticOrder& S, const Epi& E) {
;     ...
;     for (;;) {
;         const bool has_next = S.next(ui + 1, nxt);
;         const char* nA = has_next ? (const char*)g.A + (size_t)nxt.pm * tstepA + (size_t)nxt.pn * g.a_pn_step : cA; const char* nB = has_next ? (const char*)g.Bt + (size_t)nxt.pn * tstepB : cB;
; #pragma unroll 1
;         for (int t = 0; t < nt; t += 2) {
;             const bool last = (t == nt - 2);
;             const char* a1 = cA + (size_t)(t + 1) * kstep;
;             const char* a2 = last ? nA : cA + (size_t)(t + 2) * kstep; const char* b2 = last ? nB : cB + (size_t)(t + 2) * kstep;
;             const char* a3 = a2 + kstep; const char* b3 = b2 + kstep;
;             PG8_LDB(B0, 0, 0); PG8_SCHED; PG8_LDA(At, 0, 0); PG8_STAGE(PG8_SA(1, 1), a1 + hstepA, voffA);
;             PG8_WAIT_L(8); PG8_BAR; PG8_WAIT_L(0); PG8_MMA(0, 0, At, B0); PG8_BAR; PG8_SCHED;
;             PG8_LDB(B1, 0, 1); PG8_STAGE(PG8_SB(0, 0), b2, voffB);
;             PG8_BAR; PG8_WAIT_L(0); PG8_MMA(0, 1, At, B1); PG8_BAR;
;             PG8_LDA(At, 0, 1); PG8_STAGE(PG8_SA(0, 0), a2, voffA);
;             PG8_BAR; PG8_WAIT_L(0); PG8_MMA(1, 0, At, B0); PG8_BAR; PG8_SCHED;
.LBB0_1478:
	ds_read_b128 v[140:143], v150
	ds_read_b128 v[154:157], v150 offset:1024
	ds_read_b128 v[158:161], v150 offset:2048
	ds_read_b128 v[162:165], v150 offset:3072
	s_add_u32 s38, s36, 0xfffc0080
	s_addc_u32 s39, s37, -1
	s_cmp_eq_u32 s59, 12
	s_cselect_b32 s41, s25, s39
	s_cselect_b32 s40, s55, s38
	s_cselect_b32 s39, s23, s58
	s_cselect_b32 s38, s56, s57
	v_lshl_add_u64 v[144:145], s[36:37], 0, v[132:133]
	s_add_i32 m0, s35, 0xc000
	ds_read_b128 v[166:169], v151
	ds_read_b128 v[170:173], v151 offset:1024
	ds_read_b128 v[174:177], v151 offset:2048
	ds_read_b128 v[178:181], v151 offset:3072
	ds_read_b128 v[186:189], v151 offset:4096
	ds_read_b128 v[190:193], v151 offset:5120
	ds_read_b128 v[194:197], v151 offset:6144
	ds_read_b128 v[198:201], v151 offset:7168
	global_load_lds_dwordx4 v[144:145], off
	v_lshl_add_u64 v[144:145], s[36:37], 0, v[134:135]
	s_add_i32 m0, s35, 0xe000
	s_nop 0
	global_load_lds_dwordx4 v[144:145], off
	s_waitcnt lgkmcnt(8)
	s_barrier
	s_waitcnt lgkmcnt(0)
	s_setprio 1
	s_waitcnt lgkmcnt(0)
	v_mfma_f32_16x16x32_bf16 v[124:127], v[140:143], v[166:169], v[124:127]
	v_mfma_f32_16x16x32_bf16 v[120:123], v[158:161], v[166:169], v[120:123]
	v_mfma_f32_16x16x32_bf16 v[112:115], v[140:143], v[174:177], v[112:115]
	v_mfma_f32_16x16x32_bf16 v[104:107], v[158:161], v[174:177], v[104:107]
	v_mfma_f32_16x16x32_bf16 v[96:99], v[140:143], v[186:189], v[96:99]
	v_mfma_f32_16x16x32_bf16 v[88:91], v[158:161], v[186:189], v[88:91]
	v_mfma_f32_16x16x32_bf16 v[80:83], v[140:143], v[194:197], v[80:83]
	v_mfma_f32_16x16x32_bf16 v[72:75], v[158:161], v[194:197], v[72:75]
	v_mfma_f32_16x16x32_bf16 v[124:127], v[154:157], v[170:173], v[124:127]
	v_mfma_f32_16x16x32_bf16 v[120:123], v[162:165], v[170:173], v[120:123]
	v_mfma_f32_16x16x32_bf16 v[112:115], v[154:157], v[178:181], v[112:115]
	v_mfma_f32_16x16x32_bf16 v[104:107], v[162:165], v[178:181], v[104:107]
	v_mfma_f32_16x16x32_bf16 v[96:99], v[154:157], v[190:193], v[96:99]
	v_mfma_f32_16x16x32_bf16 v[88:91], v[162:165], v[190:193], v[88:91]
	v_mfma_f32_16x16x32_bf16 v[80:83], v[154:157], v[198:201], v[80:83]
	v_mfma_f32_16x16x32_bf16 v[72:75], v[162:165], v[198:201], v[72:75]
	s_setprio 0
	s_barrier
	s_add_i32 s60, s52, s42
	v_lshl_add_u64 v[144:145], s[38:39], 0, v[128:129]
	s_mov_b32 m0, s60
	ds_read_b128 v[202:205], v152
	ds_read_b128 v[206:209], v152 offset:1024
	ds_read_b128 v[210:213], v152 offset:2048
	ds_read_b128 v[214:217], v152 offset:3072
	global_load_lds_dwordx4 v[144:145], off
	v_lshl_add_u64 v[182:183], s[38:39], 0, v[130:131]
	s_add_i32 m0, s60, 0x2000
	s_nop 0
	global_load_lds_dwordx4 v[182:183], off
	s_barrier
	s_waitcnt lgkmcnt(0)
	s_setprio 1
	s_waitcnt lgkmcnt(0)
	v_mfma_f32_16x16x32_bf16 v[116:119], v[202:205], v[166:169], v[116:119]
	v_mfma_f32_16x16x32_bf16 v[108:111], v[210:213], v[166:169], v[108:111]
	v_mfma_f32_16x16x32_bf16 v[100:103], v[202:205], v[174:177], v[100:103]
	v_mfma_f32_16x16x32_bf16 v[92:95], v[210:213], v[174:177], v[92:95]
	v_mfma_f32_16x16x32_bf16 v[84:87], v[202:205], v[186:189], v[84:87]
	v_mfma_f32_16x16x32_bf16 v[76:79], v[210:213], v[186:189], v[76:79]
	v_mfma_f32_16x16x32_bf16 v[68:71], v[202:205], v[194:197], v[68:71]
	v_mfma_f32_16x16x32_bf16 v[64:67], v[210:213], v[194:197], v[64:67]
	v_mfma_f32_16x16x32_bf16 v[116:119], v[206:209], v[170:173], v[116:119]
	v_mfma_f32_16x16x32_bf16 v[108:111], v[214:217], v[170:173], v[108:111]
	v_mfma_f32_16x16x32_bf16 v[100:103], v[206:209], v[178:181], v[100:103]
	v_mfma_f32_16x16x32_bf16 v[92:95], v[214:217], v[178:181], v[92:95]
	v_mfma_f32_16x16x32_bf16 v[84:87], v[206:209], v[190:193], v[84:87]
	v_mfma_f32_16x16x32_bf16 v[76:79], v[214:217], v[190:193], v[76:79]
	v_mfma_f32_16x16x32_bf16 v[68:71], v[206:209], v[198:201], v[68:71]
	v_mfma_f32_16x16x32_bf16 v[64:67], v[214:217], v[198:201], v[64:67]
	s_setprio 0
	s_mov_b32 m0, s35
	v_lshl_add_u64 v[218:219], s[40:41], 0, v[128:129]
	s_barrier
	ds_read_b128 v[166:169], v151 offset:16384
	ds_read_b128 v[170:173], v151 offset:17408
	ds_read_b128 v[174:177], v151 offset:18432
	ds_read_b128 v[178:181], v151 offset:19456
	ds_read_b128 v[186:189], v151 offset:20480
	ds_read_b128 v[190:193], v151 offset:21504
	ds_read_b128 v[194:197], v151 offset:22528
	ds_read_b128 v[198:201], v151 offset:23552
	global_load_lds_dwordx4 v[218:219], off
	v_lshl_add_u64 v[220:221], s[40:41], 0, v[130:131]
	s_mov_b32 m0, s43
	s_nop 0
	global_load_lds_dwordx4 v[220:221], off
	s_barrier
	s_waitcnt lgkmcnt(0)
	s_setprio 1
	s_waitcnt lgkmcnt(0)
	v_mfma_f32_16x16x32_bf16 v[60:63], v[140:143], v[166:169], v[60:63]
	v_mfma_f32_16x16x32_bf16 v[56:59], v[158:161], v[166:169], v[56:59]
	v_mfma_f32_16x16x32_bf16 v[48:51], v[140:143], v[174:177], v[48:51]
	v_mfma_f32_16x16x32_bf16 v[40:43], v[158:161], v[174:177], v[40:43]
	v_mfma_f32_16x16x32_bf16 v[32:35], v[140:143], v[186:189], v[32:35]
	v_mfma_f32_16x16x32_bf16 v[24:27], v[158:161], v[186:189], v[24:27]
	v_mfma_f32_16x16x32_bf16 v[16:19], v[140:143], v[194:197], v[16:19]
	v_mfma_f32_16x16x32_bf16 v[8:11], v[158:161], v[194:197], v[8:11]
	v_mfma_f32_16x16x32_bf16 v[60:63], v[154:157], v[170:173], v[60:63]
	v_mfma_f32_16x16x32_bf16 v[56:59], v[162:165], v[170:173], v[56:59]
	v_mfma_f32_16x16x32_bf16 v[48:51], v[154:157], v[178:181], v[48:51]
	v_mfma_f32_16x16x32_bf16 v[40:43], v[162:165], v[178:181], v[40:43]
	v_mfma_f32_16x16x32_bf16 v[32:35], v[154:157], v[190:193], v[32:35]
	v_mfma_f32_16x16x32_bf16 v[24:27], v[162:165], v[190:193], v[24:27]
	v_mfma_f32_16x16x32_bf16 v[16:19], v[154:157], v[198:201], v[16:19]
	v_mfma_f32_16x16x32_bf16 v[8:11], v[162:165], v[198:201], v[8:11]
	s_setprio 0
	s_barrier
; #define PG8_STAGE(bufoff, gbase, voff) do { _Pragma("unroll") for (int _i = 0; _i < 2; ++_i) \
;         __builtin_amdgcn_global_load_lds((const unsigned*)((const char*)(gbase) + (voff)[_i]), (LAS unsigned*)(lds + (bufoff) + ldsw + _i * 8192), 16, 0, 0); } while (0)
; #define PG8_LDA(dst, b, h) do { _Pragma("unroll") for (int m = 0; m < 4; ++m) _Pragma("unroll") for (int k = 0; k < 2; ++k) dst[m][k] = *(const LAS bf16x8*)(lds + PG8_SA(b, h) + aoff + m * 2048 + k * 1024); } while (0)
; #define PG8_LDB(dst, b, h) do { _Pragma("unroll") for (int n = 0; n < 2; ++n) _Pragma("unroll") for (int k = 0; k < 2; ++k) dst[n][k] = *(const LAS bf16x8*)(lds + PG8_SB(b, h) + boff + n * 2048 + k * 1024); } while (0)
; #define PG8_MMA(ai, bj, At, Bt) do { __builtin_amdgcn_s_setprio(1); _Pragma("unroll") for (int m = 0; m < 4; ++m) _Pragma("unroll") for (int n = 0; n < 2; ++n) _Pragma("unroll") for (int k = 0; k < 2; ++k) \
;         acc[ai][bj][m][n] = __builtin_amdgcn_mfma_f32_16x16x32_bf16(Bt[n][k], At[m][k], acc[ai][bj][m][n], 0, 0, 0); __builtin_amdgcn_s_setprio(0); } while (0)
; #define PG8_WAIT_V(n) asm volatile("s_waitcnt vmcnt(" #n ")" ::: "memory")
; #define PG8_WAIT_L(n) asm volatile("s_waitcnt lgkmcnt(" #n ")" ::: "memory")
; #define PG8_BAR __builtin_amdgcn_s_barrier()
; #define PG8_SCHED __builtin_amdgcn_sched_barrier(0)
; template <class Epi>
; __device__ __forceinline__ void gemm_phase(LAS unsigned char* lds, const Gemm g, const StaticOrder& S, const Epi& E) {
;     ...
;             PG8_BAR; PG8_WAIT_L(0); PG8_MMA(1, 0, At, B0); PG8_BAR; PG8_SCHED;
;             PG8_STAGE(PG8_SB(0, 1), b2 + hstepB, voffB);
;             PG8_WAIT_V(6); PG8_BAR; PG8_MMA(1, 1, At, B1); PG8_BAR;
;             PG8_LDB(B0, 1, 0); PG8_SCHED; PG8_LDA(At, 1, 0); PG8_STAGE(PG8_SA(0, 1), a2 + hstepA, voffA);
;             PG8_WAIT_L(8); PG8_BAR; PG8_WAIT_L(0); PG8_MMA(0, 0, At, B0); PG8_BAR; PG8_SCHED;
;             PG8_LDB(B1, 1, 1); PG8_STAGE(PG8_SB(1, 0), b3, voffB);
;             PG8_BAR; PG8_WAIT_L(0); PG8_MMA(0, 1, At, B1); PG8_BAR;
;             PG8_LDA(At, 1, 1); PG8_STAGE(PG8_SA(1, 0), a3, voffA);
;             PG8_BAR; PG8_WAIT_L(0); PG8_MMA(1, 0, At, B0); PG8_BAR; PG8_SCHED;
	s_add_u32 s60, s38, 0x40000
	s_addc_u32 s61, s39, 0
	s_add_i32 s62, s53, s42
	v_lshl_add_u64 v[140:141], s[60:61], 0, v[128:129]
	s_mov_b32 m0, s62
	s_nop 0
	global_load_lds_dwordx4 v[140:141], off
	v_lshl_add_u64 v[140:141], s[60:61], 0, v[130:131]
	s_add_i32 m0, s62, 0x2000
	s_nop 0
	global_load_lds_dwordx4 v[140:141], off
	s_waitcnt vmcnt(6)
	s_barrier
	s_setprio 1
	v_mfma_f32_16x16x32_bf16 v[52:55], v[202:205], v[166:169], v[52:55]
	v_mfma_f32_16x16x32_bf16 v[44:47], v[210:213], v[166:169], v[44:47]
	v_mfma_f32_16x16x32_bf16 v[36:39], v[202:205], v[174:177], v[36:39]
	v_mfma_f32_16x16x32_bf16 v[28:31], v[210:213], v[174:177], v[28:31]
	v_mfma_f32_16x16x32_bf16 v[20:23], v[202:205], v[186:189], v[20:23]
	v_mfma_f32_16x16x32_bf16 v[12:15], v[210:213], v[186:189], v[12:15]
	v_mfma_f32_16x16x32_bf16 v[4:7], v[202:205], v[194:197], v[4:7]
	v_mfma_f32_16x16x32_bf16 v[0:3], v[210:213], v[194:197], v[0:3]
	v_mfma_f32_16x16x32_bf16 v[52:55], v[206:209], v[170:173], v[52:55]
	v_mfma_f32_16x16x32_bf16 v[44:47], v[214:217], v[170:173], v[44:47]
	v_mfma_f32_16x16x32_bf16 v[36:39], v[206:209], v[178:181], v[36:39]
	v_mfma_f32_16x16x32_bf16 v[28:31], v[214:217], v[178:181], v[28:31]
	v_mfma_f32_16x16x32_bf16 v[20:23], v[206:209], v[190:193], v[20:23]
	v_mfma_f32_16x16x32_bf16 v[12:15], v[214:217], v[190:193], v[12:15]
	v_mfma_f32_16x16x32_bf16 v[4:7], v[206:209], v[198:201], v[4:7]
	v_mfma_f32_16x16x32_bf16 v[0:3], v[214:217], v[198:201], v[0:3]
	s_setprio 0
	s_add_i32 s60, 0, 0x18000
	v_add_u32_e32 v153, s60, v148
	s_barrier
	ds_read_b128 v[140:143], v153
	ds_read_b128 v[154:157], v153 offset:1024
	ds_read_b128 v[158:161], v153 offset:2048
	ds_read_b128 v[162:165], v153 offset:3072
	s_add_u32 s40, s40, 0x40000
	s_addc_u32 s41, s41, 0
	s_mov_b32 m0, s44
	v_lshl_add_u64 v[202:203], s[40:41], 0, v[128:129]
	ds_read_b128 v[166:169], v151 offset:32768
	ds_read_b128 v[170:173], v151 offset:33792
	ds_read_b128 v[174:177], v151 offset:34816
	ds_read_b128 v[178:181], v151 offset:35840
	ds_read_b128 v[186:189], v151 offset:36864
	ds_read_b128 v[190:193], v151 offset:37888
	ds_read_b128 v[194:197], v151 offset:38912
	ds_read_b128 v[198:201], v151 offset:39936
	global_load_lds_dwordx4 v[202:203], off
	v_lshl_add_u64 v[202:203], s[40:41], 0, v[130:131]
	s_mov_b32 m0, s45
	s_nop 0
	global_load_lds_dwordx4 v[202:203], off
	s_waitcnt lgkmcnt(8)
	s_barrier
	s_waitcnt lgkmcnt(0)
	s_setprio 1
	s_waitcnt lgkmcnt(0)
	v_mfma_f32_16x16x32_bf16 v[124:127], v[140:143], v[166:169], v[124:127]
	v_mfma_f32_16x16x32_bf16 v[120:123], v[158:161], v[166:169], v[120:123]
	v_mfma_f32_16x16x32_bf16 v[112:115], v[140:143], v[174:177], v[112:115]
	v_mfma_f32_16x16x32_bf16 v[104:107], v[158:161], v[174:177], v[104:107]
	v_mfma_f32_16x16x32_bf16 v[96:99], v[140:143], v[186:189], v[96:99]
	v_mfma_f32_16x16x32_bf16 v[88:91], v[158:161], v[186:189], v[88:91]
	v_mfma_f32_16x16x32_bf16 v[80:83], v[140:143], v[194:197], v[80:83]
	v_mfma_f32_16x16x32_bf16 v[72:75], v[158:161], v[194:197], v[72:75]
	v_mfma_f32_16x16x32_bf16 v[124:127], v[154:157], v[170:173], v[124:127]
	v_mfma_f32_16x16x32_bf16 v[120:123], v[162:165], v[170:173], v[120:123]
	v_mfma_f32_16x16x32_bf16 v[112:115], v[154:157], v[178:181], v[112:115]
	v_mfma_f32_16x16x32_bf16 v[104:107], v[162:165], v[178:181], v[104:107]
	v_mfma_f32_16x16x32_bf16 v[96:99], v[154:157], v[190:193], v[96:99]
	v_mfma_f32_16x16x32_bf16 v[88:91], v[162:165], v[190:193], v[88:91]
	v_mfma_f32_16x16x32_bf16 v[80:83], v[154:157], v[198:201], v[80:83]
	v_mfma_f32_16x16x32_bf16 v[72:75], v[162:165], v[198:201], v[72:75]
	s_setprio 0
	s_barrier
	s_add_i32 s40, 0, 0x1c000
	s_add_i32 s41, s60, s42
	v_add_u32_e32 v153, s40, v148
	v_lshl_add_u64 v[144:145], v[144:145], 0, s[12:13]
	s_mov_b32 m0, s41
	ds_read_b128 v[202:205], v153
	ds_read_b128 v[206:209], v153 offset:1024
	ds_read_b128 v[210:213], v153 offset:2048
	ds_read_b128 v[214:217], v153 offset:3072
	global_load_lds_dwordx4 v[144:145], off
	v_lshl_add_u64 v[144:145], v[182:183], 0, s[12:13]
	s_add_i32 m0, s41, 0x2000
	s_nop 0
	global_load_lds_dwordx4 v[144:145], off
	s_barrier
	s_waitcnt lgkmcnt(0)
	s_setprio 1
	s_waitcnt lgkmcnt(0)
	v_mfma_f32_16x16x32_bf16 v[116:119], v[202:205], v[166:169], v[116:119]
	v_mfma_f32_16x16x32_bf16 v[108:111], v[210:213], v[166:169], v[108:111]
	v_mfma_f32_16x16x32_bf16 v[100:103], v[202:205], v[174:177], v[100:103]
	v_mfma_f32_16x16x32_bf16 v[92:95], v[210:213], v[174:177], v[92:95]
	v_mfma_f32_16x16x32_bf16 v[84:87], v[202:205], v[186:189], v[84:87]
	v_mfma_f32_16x16x32_bf16 v[76:79], v[210:213], v[186:189], v[76:79]
	v_mfma_f32_16x16x32_bf16 v[68:71], v[202:205], v[194:197], v[68:71]
	v_mfma_f32_16x16x32_bf16 v[64:67], v[210:213], v[194:197], v[64:67]
	v_mfma_f32_16x16x32_bf16 v[116:119], v[206:209], v[170:173], v[116:119]
	v_mfma_f32_16x16x32_bf16 v[108:111], v[214:217], v[170:173], v[108:111]
	v_mfma_f32_16x16x32_bf16 v[100:103], v[206:209], v[178:181], v[100:103]
	v_mfma_f32_16x16x32_bf16 v[92:95], v[214:217], v[178:181], v[92:95]
	v_mfma_f32_16x16x32_bf16 v[84:87], v[206:209], v[190:193], v[84:87]
	v_mfma_f32_16x16x32_bf16 v[76:79], v[214:217], v[190:193], v[76:79]
	v_mfma_f32_16x16x32_bf16 v[68:71], v[206:209], v[198:201], v[68:71]
	v_mfma_f32_16x16x32_bf16 v[64:67], v[214:217], v[198:201], v[64:67]
	s_setprio 0
	s_mov_b32 m0, s47
	v_lshl_add_u64 v[144:145], v[218:219], 0, s[12:13]
	s_barrier
	ds_read_b128 v[166:169], v151 offset:49152
	ds_read_b128 v[170:173], v151 offset:50176
	ds_read_b128 v[174:177], v151 offset:51200
	ds_read_b128 v[178:181], v151 offset:52224
	ds_read_b128 v[186:189], v151 offset:53248
	ds_read_b128 v[190:193], v151 offset:54272
	ds_read_b128 v[194:197], v151 offset:55296
	ds_read_b128 v[198:201], v151 offset:56320
	global_load_lds_dwordx4 v[144:145], off
	v_lshl_add_u64 v[144:145], v[220:221], 0, s[12:13]
	s_mov_b32 m0, s50
	s_nop 0
	global_load_lds_dwordx4 v[144:145], off
	s_barrier
; __device__ __forceinline__ unsigned cvt_pk_bf16(float lo, float hi) { const f32v2_t v = {lo, hi}; const bf16v2_t r = __builtin_convertvector(v, bf16v2_t); return __builtin_bit_cast(unsigned, r); }
; __device__ __forceinline__ float bf2f(short b) { return __uint_as_float(((unsigned)(unsigned short)b) << 16); }
; #define PG8_LDA(dst, b, h) do { _Pragma("unroll") for (int m = 0; m < 4; ++m) _Pragma("unroll") for (int k = 0; k < 2; ++k) dst[m][k] = *(const LAS bf16x8*)(lds + PG8_SA(b, h) + aoff + m * 2048 + k * 1024); } while (0)
; template <class Epi>
; __device__ __forceinline__ void gemm_phase(LAS unsigned char* lds, const Gemm g, const StaticOrder& S, const Epi& E) {
;     ...
;             PG8_LDA(At, 1, 1); PG8_STAGE(PG8_SA(1, 0), a3, voffA);
;             PG8_BAR; PG8_WAIT_L(0); PG8_MMA(1, 0, At, B0); PG8_BAR; PG8_SCHED;
;             PG8_STAGE(PG8_SB(1, 1), b3 + hstepB, voffB);
;             PG8_WAIT_V(6); PG8_BAR; PG8_MMA(1, 1, At, B1); PG8_BAR;
;         }
;         E(acc, cur, wr, wc, fr, fq);
;         if (!has_next) break;
;     __device__ __forceinline__ void operator()(const f32x4 (&acc)[2][2][4][2], const Unit& u, int wr, int wc, int fr, int fq) const {
;         const int row0 = u.pm * BM + wr * 64 + fr, col0 = u.pn * BM + wc * 32 + 4 * fq;
;         const float* bb = (u.pm < 64) ? base0 : base1 - (size_t)MP * DM;
; #pragma unroll
;         for (int ai = 0; ai < 2; ++ai)
; #pragma unroll
;             for (int m = 0; m < 4; ++m) { const size_t ro = (size_t)(row0 + ai * HALF + m * 16) * DM + col0; float ss = 0.f;
; #pragma unroll
;                 for (int bj = 0; bj < 2; ++bj)
; #pragma unroll
;                     for (int n = 0; n < 2; ++n) {
;                         if constexpr (NORM) {
;                             const f32x4 bv = *(const f32x4*)(bb + ro + bj * HALF + n * 16); const f32x4 v = acc[ai][bj][m][n] + bv;
;                             ss += (v[0] * v[0] + v[1] * v[1]) + (v[2] * v[2] + v[3] * v[3]);
;                             u32x2 w; w.x = cvt_pk_bf16(v[0], v[1]); w.y = cvt_pk_bf16(v[2], v[3]); *(u32x2*)(a3 + ro + bj * HALF + n * 16) = w;
;                         } else {
;                             const bf16x4 hb = *(const bf16x4*)(a3 + ro + bj * HALF + n * 16);
;                             *(f32x4*)(out + ro + bj * HALF + n * 16) = acc[ai][bj][m][n] + (f32x4){bf2f(hb[0]), bf2f(hb[1]), bf2f(hb[2]), bf2f(hb[3])}; } }
	s_waitcnt lgkmcnt(0)
	s_setprio 1
	s_waitcnt lgkmcnt(0)
	v_mfma_f32_16x16x32_bf16 v[60:63], v[140:143], v[166:169], v[60:63]
	v_mfma_f32_16x16x32_bf16 v[56:59], v[158:161], v[166:169], v[56:59]
	v_mfma_f32_16x16x32_bf16 v[48:51], v[140:143], v[174:177], v[48:51]
	v_mfma_f32_16x16x32_bf16 v[40:43], v[158:161], v[174:177], v[40:43]
	v_mfma_f32_16x16x32_bf16 v[32:35], v[140:143], v[186:189], v[32:35]
	v_mfma_f32_16x16x32_bf16 v[24:27], v[158:161], v[186:189], v[24:27]
	v_mfma_f32_16x16x32_bf16 v[16:19], v[140:143], v[194:197], v[16:19]
	v_mfma_f32_16x16x32_bf16 v[8:11], v[158:161], v[194:197], v[8:11]
	v_mfma_f32_16x16x32_bf16 v[60:63], v[154:157], v[170:173], v[60:63]
	v_mfma_f32_16x16x32_bf16 v[56:59], v[162:165], v[170:173], v[56:59]
	v_mfma_f32_16x16x32_bf16 v[48:51], v[154:157], v[178:181], v[48:51]
	v_mfma_f32_16x16x32_bf16 v[40:43], v[162:165], v[178:181], v[40:43]
	v_mfma_f32_16x16x32_bf16 v[32:35], v[154:157], v[190:193], v[32:35]
	v_mfma_f32_16x16x32_bf16 v[24:27], v[162:165], v[190:193], v[24:27]
	v_mfma_f32_16x16x32_bf16 v[16:19], v[154:157], v[198:201], v[16:19]
	v_mfma_f32_16x16x32_bf16 v[8:11], v[162:165], v[198:201], v[8:11]
	s_setprio 0
	s_barrier
	s_add_u32 s38, s38, 0x40080
	s_addc_u32 s39, s39, 0
	s_add_i32 s40, s40, s42
	v_lshl_add_u64 v[140:141], s[38:39], 0, v[128:129]
	s_mov_b32 m0, s40
	s_nop 0
	global_load_lds_dwordx4 v[140:141], off
	v_lshl_add_u64 v[140:141], s[38:39], 0, v[130:131]
	s_add_i32 m0, s40, 0x2000
	s_nop 0
	global_load_lds_dwordx4 v[140:141], off
	s_waitcnt vmcnt(6)
	s_barrier
	s_setprio 1
	v_mfma_f32_16x16x32_bf16 v[52:55], v[202:205], v[166:169], v[52:55]
	v_mfma_f32_16x16x32_bf16 v[44:47], v[210:213], v[166:169], v[44:47]
	v_mfma_f32_16x16x32_bf16 v[36:39], v[202:205], v[174:177], v[36:39]
	v_mfma_f32_16x16x32_bf16 v[28:31], v[210:213], v[174:177], v[28:31]
	v_mfma_f32_16x16x32_bf16 v[20:23], v[202:205], v[186:189], v[20:23]
	v_mfma_f32_16x16x32_bf16 v[12:15], v[210:213], v[186:189], v[12:15]
	v_mfma_f32_16x16x32_bf16 v[4:7], v[202:205], v[194:197], v[4:7]
	v_mfma_f32_16x16x32_bf16 v[0:3], v[210:213], v[194:197], v[0:3]
	v_mfma_f32_16x16x32_bf16 v[52:55], v[206:209], v[170:173], v[52:55]
	v_mfma_f32_16x16x32_bf16 v[44:47], v[214:217], v[170:173], v[44:47]
	v_mfma_f32_16x16x32_bf16 v[36:39], v[206:209], v[178:181], v[36:39]
	v_mfma_f32_16x16x32_bf16 v[28:31], v[214:217], v[178:181], v[28:31]
	v_mfma_f32_16x16x32_bf16 v[20:23], v[206:209], v[190:193], v[20:23]
	v_mfma_f32_16x16x32_bf16 v[12:15], v[214:217], v[190:193], v[12:15]
	v_mfma_f32_16x16x32_bf16 v[4:7], v[206:209], v[198:201], v[4:7]
	v_mfma_f32_16x16x32_bf16 v[0:3], v[214:217], v[198:201], v[0:3]
	s_setprio 0
	s_add_i32 s59, s59, 2
	s_add_u32 s36, s36, 0x100
	s_addc_u32 s37, s37, 0
	s_add_u32 s57, s57, 0x100
	s_addc_u32 s58, s58, 0
	s_cmp_gt_u32 s59, 13
	s_barrier
	s_cbranch_scc0 .LBB0_1478
	v_lshl_add_u32 v144, s34, 8, v147
	v_lshl_or_b32 v142, s54, 8, v149
	v_ashrrev_i32_e32 v145, 31, v144
	v_ashrrev_i32_e32 v143, 31, v142
	v_lshlrev_b64 v[140:141], 10, v[144:145]
	v_lshl_add_u64 v[140:141], v[140:141], 0, v[142:143]
	v_lshl_add_u64 v[154:155], v[140:141], 1, s[4:5]
	global_load_dwordx2 v[156:157], v[154:155], off
	v_lshl_add_u64 v[158:159], v[140:141], 2, s[48:49]
	s_and_b64 vcc, exec, s[0:1]
	s_mov_b32 s54, s22
	s_mov_b32 s34, s24
	s_mov_b64 s[38:39], s[28:29]
	s_mov_b64 s[36:37], s[26:27]
	s_waitcnt vmcnt(0)
	v_and_b32_e32 v161, 0xffff0000, v157
	v_lshlrev_b32_e32 v160, 16, v157
	v_and_b32_e32 v157, 0xffff0000, v156
	v_lshlrev_b32_e32 v156, 16, v156
	v_pk_add_f32 v[124:125], v[124:125], v[156:157]
	v_pk_add_f32 v[126:127], v[126:127], v[160:161]
	global_store_dwordx4 v[158:159], v[124:127], off nt
	global_load_dwordx2 v[124:125], v[154:155], off offset:32
	s_waitcnt vmcnt(0)
	v_and_b32_e32 v127, 0xffff0000, v125
	v_lshlrev_b32_e32 v126, 16, v125
	v_and_b32_e32 v125, 0xffff0000, v124
	v_lshlrev_b32_e32 v124, 16, v124
	v_pk_add_f32 v[120:121], v[120:121], v[124:125]
	v_pk_add_f32 v[122:123], v[122:123], v[126:127]
	global_store_dwordx4 v[158:159], v[120:123], off offset:64 nt
	global_load_dwordx2 v[120:121], v[154:155], off offset:256
	s_waitcnt vmcnt(0)
	v_and_b32_e32 v123, 0xffff0000, v121
	v_lshlrev_b32_e32 v122, 16, v121
	v_and_b32_e32 v121, 0xffff0000, v120
	v_lshlrev_b32_e32 v120, 16, v120
	v_pk_add_f32 v[116:117], v[116:117], v[120:121]
	v_pk_add_f32 v[118:119], v[118:119], v[122:123]
	global_store_dwordx4 v[158:159], v[116:119], off offset:512 nt
	global_load_dwordx2 v[116:117], v[154:155], off offset:288
	s_waitcnt vmcnt(0)
	v_and_b32_e32 v123, 0xffff0000, v117
	v_or_b32_e32 v118, 16, v144
	v_ashrrev_i32_e32 v119, 31, v118
	v_lshlrev_b64 v[118:119], 10, v[118:119]
	v_lshlrev_b32_e32 v122, 16, v117
	v_and_b32_e32 v117, 0xffff0000, v116
	v_lshlrev_b32_e32 v116, 16, v116
	v_lshl_add_u64 v[118:119], v[118:119], 0, v[142:143]
	v_pk_add_f32 v[108:109], v[108:109], v[116:117]
	v_pk_add_f32 v[110:111], v[110:111], v[122:123]
	v_lshl_add_u64 v[120:121], v[118:119], 1, s[4:5]
	global_store_dwordx4 v[158:159], v[108:111], off offset:576 nt
	global_load_dwordx2 v[108:109], v[120:121], off
	v_lshl_add_u64 v[116:117], v[118:119], 2, s[48:49]
	s_waitcnt vmcnt(0)
	v_and_b32_e32 v111, 0xffff0000, v109
	v_lshlrev_b32_e32 v110, 16, v109
	v_and_b32_e32 v109, 0xffff0000, v108
	v_lshlrev_b32_e32 v108, 16, v108
	v_pk_add_f32 v[108:109], v[112:113], v[108:109]
	v_pk_add_f32 v[110:111], v[114:115], v[110:111]
	global_store_dwordx4 v[116:117], v[108:111], off nt
	global_load_dwordx2 v[108:109], v[120:121], off offset:32
	s_waitcnt vmcnt(0)
; __device__ __forceinline__ unsigned cvt_pk_bf16(float lo, float hi) { const f32v2_t v = {lo, hi}; const bf16v2_t r = __builtin_convertvector(v, bf16v2_t); return __builtin_bit_cast(unsigned, r); }
; __device__ __forceinline__ float bf2f(short b) { return __uint_as_float(((unsigned)(unsigned short)b) << 16); }
;     __device__ __forceinline__ void operator()(const f32x4 (&acc)[2][2][4][2], const Unit& u, int wr, int wc, int fr, int fq) const {
;     ...
;             for (int m = 0; m < 4; ++m) { const size_t ro = (size_t)(row0 + ai * HALF + m * 16) * DM + col0; float ss = 0.f;
; #pragma unroll
;                 for (int bj = 0; bj < 2; ++bj)
; #pragma unroll
;                     for (int n = 0; n < 2; ++n) {
;                         if constexpr (NORM) {
;                             const f32x4 bv = *(const f32x4*)(bb + ro + bj * HALF + n * 16); const f32x4 v = acc[ai][bj][m][n] + bv;
;                             ss += (v[0] * v[0] + v[1] * v[1]) + (v[2] * v[2] + v[3] * v[3]);
;                             u32x2 w; w.x = cvt_pk_bf16(v[0], v[1]); w.y = cvt_pk_bf16(v[2], v[3]); *(u32x2*)(a3 + ro + bj * HALF + n * 16) = w;
;                         } else {
;                             const bf16x4 hb = *(const bf16x4*)(a3 + ro + bj * HALF + n * 16);
;                             *(f32x4*)(out + ro + bj * HALF + n * 16) = acc[ai][bj][m][n] + (f32x4){bf2f(hb[0]), bf2f(hb[1]), bf2f(hb[2]), bf2f(hb[3])}; } }
	v_and_b32_e32 v111, 0xffff0000, v109
	v_lshlrev_b32_e32 v110, 16, v109
	v_and_b32_e32 v109, 0xffff0000, v108
	v_lshlrev_b32_e32 v108, 16, v108
	v_pk_add_f32 v[104:105], v[104:105], v[108:109]
	v_pk_add_f32 v[106:107], v[106:107], v[110:111]
	global_store_dwordx4 v[116:117], v[104:107], off offset:64 nt
	global_load_dwordx2 v[104:105], v[120:121], off offset:256
	s_waitcnt vmcnt(0)
	v_and_b32_e32 v107, 0xffff0000, v105
	v_lshlrev_b32_e32 v106, 16, v105
	v_and_b32_e32 v105, 0xffff0000, v104
	v_lshlrev_b32_e32 v104, 16, v104
	v_pk_add_f32 v[100:101], v[100:101], v[104:105]
	v_pk_add_f32 v[102:103], v[102:103], v[106:107]
	global_store_dwordx4 v[116:117], v[100:103], off offset:512 nt
	global_load_dwordx2 v[100:101], v[120:121], off offset:288
	s_waitcnt vmcnt(0)
	v_and_b32_e32 v107, 0xffff0000, v101
	v_or_b32_e32 v102, 32, v144
	v_ashrrev_i32_e32 v103, 31, v102
	v_lshlrev_b64 v[102:103], 10, v[102:103]
	v_lshlrev_b32_e32 v106, 16, v101
	v_and_b32_e32 v101, 0xffff0000, v100
	v_lshlrev_b32_e32 v100, 16, v100
	v_lshl_add_u64 v[102:103], v[102:103], 0, v[142:143]
	v_pk_add_f32 v[92:93], v[92:93], v[100:101]
	v_pk_add_f32 v[94:95], v[94:95], v[106:107]
	v_lshl_add_u64 v[104:105], v[102:103], 1, s[4:5]
	global_store_dwordx4 v[116:117], v[92:95], off offset:576 nt
	global_load_dwordx2 v[92:93], v[104:105], off
	v_lshl_add_u64 v[100:101], v[102:103], 2, s[48:49]
	s_waitcnt vmcnt(0)
	v_and_b32_e32 v95, 0xffff0000, v93
	v_lshlrev_b32_e32 v94, 16, v93
	v_and_b32_e32 v93, 0xffff0000, v92
	v_lshlrev_b32_e32 v92, 16, v92
	v_pk_add_f32 v[92:93], v[96:97], v[92:93]
	v_pk_add_f32 v[94:95], v[98:99], v[94:95]
	global_store_dwordx4 v[100:101], v[92:95], off nt
	global_load_dwordx2 v[92:93], v[104:105], off offset:32
	s_waitcnt vmcnt(0)
	v_and_b32_e32 v95, 0xffff0000, v93
	v_lshlrev_b32_e32 v94, 16, v93
	v_and_b32_e32 v93, 0xffff0000, v92
	v_lshlrev_b32_e32 v92, 16, v92
	v_pk_add_f32 v[88:89], v[88:89], v[92:93]
	v_pk_add_f32 v[90:91], v[90:91], v[94:95]
	global_store_dwordx4 v[100:101], v[88:91], off offset:64 nt
	global_load_dwordx2 v[88:89], v[104:105], off offset:256
	s_waitcnt vmcnt(0)
	v_and_b32_e32 v91, 0xffff0000, v89
	v_lshlrev_b32_e32 v90, 16, v89
	v_and_b32_e32 v89, 0xffff0000, v88
	v_lshlrev_b32_e32 v88, 16, v88
	v_pk_add_f32 v[84:85], v[84:85], v[88:89]
	v_pk_add_f32 v[86:87], v[86:87], v[90:91]
	global_store_dwordx4 v[100:101], v[84:87], off offset:512 nt
	global_load_dwordx2 v[84:85], v[104:105], off offset:288
	s_waitcnt vmcnt(0)
	v_and_b32_e32 v91, 0xffff0000, v85
	v_or_b32_e32 v86, 48, v144
	v_ashrrev_i32_e32 v87, 31, v86
	v_lshlrev_b64 v[86:87], 10, v[86:87]
	v_lshlrev_b32_e32 v90, 16, v85
	v_and_b32_e32 v85, 0xffff0000, v84
	v_lshlrev_b32_e32 v84, 16, v84
	v_lshl_add_u64 v[86:87], v[86:87], 0, v[142:143]
	v_pk_add_f32 v[76:77], v[76:77], v[84:85]
	v_pk_add_f32 v[78:79], v[78:79], v[90:91]
	v_lshl_add_u64 v[88:89], v[86:87], 1, s[4:5]
	global_store_dwordx4 v[100:101], v[76:79], off offset:576 nt
	global_load_dwordx2 v[76:77], v[88:89], off
	v_lshl_add_u64 v[84:85], v[86:87], 2, s[48:49]
	s_waitcnt vmcnt(0)
	v_and_b32_e32 v79, 0xffff0000, v77
	v_lshlrev_b32_e32 v78, 16, v77
	v_and_b32_e32 v77, 0xffff0000, v76
	v_lshlrev_b32_e32 v76, 16, v76
	v_pk_add_f32 v[76:77], v[80:81], v[76:77]
	v_pk_add_f32 v[78:79], v[82:83], v[78:79]
	global_store_dwordx4 v[84:85], v[76:79], off nt
	global_load_dwordx2 v[76:77], v[88:89], off offset:32
	s_waitcnt vmcnt(0)
	v_and_b32_e32 v79, 0xffff0000, v77
	v_lshlrev_b32_e32 v78, 16, v77
	v_and_b32_e32 v77, 0xffff0000, v76
	v_lshlrev_b32_e32 v76, 16, v76
	v_pk_add_f32 v[72:73], v[72:73], v[76:77]
	v_pk_add_f32 v[74:75], v[74:75], v[78:79]
	global_store_dwordx4 v[84:85], v[72:75], off offset:64 nt
	global_load_dwordx2 v[72:73], v[88:89], off offset:256
	s_waitcnt vmcnt(0)
	v_and_b32_e32 v75, 0xffff0000, v73
	v_lshlrev_b32_e32 v74, 16, v73
	v_and_b32_e32 v73, 0xffff0000, v72
	v_lshlrev_b32_e32 v72, 16, v72
	v_pk_add_f32 v[68:69], v[68:69], v[72:73]
	v_pk_add_f32 v[70:71], v[70:71], v[74:75]
	global_store_dwordx4 v[84:85], v[68:71], off offset:512 nt
	global_load_dwordx2 v[68:69], v[88:89], off offset:288
	s_waitcnt vmcnt(0)
	v_and_b32_e32 v75, 0xffff0000, v69
	v_lshlrev_b32_e32 v74, 16, v69
	v_and_b32_e32 v69, 0xffff0000, v68
	v_lshlrev_b32_e32 v68, 16, v68
	v_lshl_add_u64 v[70:71], v[140:141], 0, s[14:15]
	v_pk_add_f32 v[64:65], v[64:65], v[68:69]
	v_pk_add_f32 v[66:67], v[66:67], v[74:75]
	v_lshl_add_u64 v[72:73], v[70:71], 1, s[4:5]
	global_store_dwordx4 v[84:85], v[64:67], off offset:576 nt
	global_load_dwordx2 v[64:65], v[72:73], off
	s_waitcnt vmcnt(0)
	v_and_b32_e32 v69, 0xffff0000, v65
	v_lshlrev_b32_e32 v68, 16, v65
	v_and_b32_e32 v65, 0xffff0000, v64
	v_lshlrev_b32_e32 v64, 16, v64
	v_lshl_add_u64 v[66:67], v[70:71], 2, s[48:49]
	v_pk_add_f32 v[60:61], v[60:61], v[64:65]
	v_pk_add_f32 v[62:63], v[62:63], v[68:69]
	global_store_dwordx4 v[66:67], v[60:63], off nt
	global_load_dwordx2 v[60:61], v[72:73], off offset:32
	s_waitcnt vmcnt(0)
	v_and_b32_e32 v63, 0xffff0000, v61
	v_lshlrev_b32_e32 v62, 16, v61
	v_and_b32_e32 v61, 0xffff0000, v60
	v_lshlrev_b32_e32 v60, 16, v60
	v_pk_add_f32 v[56:57], v[56:57], v[60:61]
	v_pk_add_f32 v[58:59], v[58:59], v[62:63]
	global_store_dwordx4 v[66:67], v[56:59], off offset:64 nt
	global_load_dwordx2 v[56:57], v[72:73], off offset:256
	s_waitcnt vmcnt(0)
; __device__ __forceinline__ unsigned cvt_pk_bf16(float lo, float hi) { const f32v2_t v = {lo, hi}; const bf16v2_t r = __builtin_convertvector(v, bf16v2_t); return __builtin_bit_cast(unsigned, r); }
; __device__ __forceinline__ float bf2f(short b) { return __uint_as_float(((unsigned)(unsigned short)b) << 16); }
; #define PG8_WAIT_V(n) asm volatile("s_waitcnt vmcnt(" #n ")" ::: "memory")
; #define PG8_BAR __builtin_amdgcn_s_barrier()
; template <class Epi>
; __device__ __forceinline__ void gemm_phase(LAS unsigned char* lds, const Gemm g, const StaticOrder& S, const Epi& E) {
;     ...
;         if (!has_next) break;
; #pragma unroll
;         for (int a = 0; a < 2; ++a)
; #pragma unroll
;             for (int b = 0; b < 2; ++b)
; #pragma unroll
;                 for (int m = 0; m < 4; ++m)
; #pragma unroll
;                     for (int n = 0; n < 2; ++n) acc[a][b][m][n] = (f32x4){0.f, 0.f, 0.f, 0.f};
;         cur = nxt; cA = nA; cB = nB; ++ui;
;     }
;     PG8_WAIT_V(0);
;     if (wr == 0) PG8_BAR;
;     PG8_BAR;
;     __device__ __forceinline__ void operator()(const f32x4 (&acc)[2][2][4][2], const Unit& u, int wr, int wc, int fr, int fq) const {
;     ...
;             for (int m = 0; m < 4; ++m) { const size_t ro = (size_t)(row0 + ai * HALF + m * 16) * DM + col0; float ss = 0.f;
; #pragma unroll
;                 for (int bj = 0; bj < 2; ++bj)
; #pragma unroll
;                     for (int n = 0; n < 2; ++n) {
;                         if constexpr (NORM) {
;                             const f32x4 bv = *(const f32x4*)(bb + ro + bj * HALF + n * 16); const f32x4 v = acc[ai][bj][m][n] + bv;
;                             ss += (v[0] * v[0] + v[1] * v[1]) + (v[2] * v[2] + v[3] * v[3]);
;                             u32x2 w; w.x = cvt_pk_bf16(v[0], v[1]); w.y = cvt_pk_bf16(v[2], v[3]); *(u32x2*)(a3 + ro + bj * HALF + n * 16) = w;
;                         } else {
;                             const bf16x4 hb = *(const bf16x4*)(a3 + ro + bj * HALF + n * 16);
;                             *(f32x4*)(out + ro + bj * HALF + n * 16) = acc[ai][bj][m][n] + (f32x4){bf2f(hb[0]), bf2f(hb[1]), bf2f(hb[2]), bf2f(hb[3])}; } }
	v_and_b32_e32 v59, 0xffff0000, v57
	v_lshlrev_b32_e32 v58, 16, v57
	v_and_b32_e32 v57, 0xffff0000, v56
	v_lshlrev_b32_e32 v56, 16, v56
	v_pk_add_f32 v[52:53], v[52:53], v[56:57]
	v_pk_add_f32 v[54:55], v[54:55], v[58:59]
	global_store_dwordx4 v[66:67], v[52:55], off offset:512 nt
	global_load_dwordx2 v[52:53], v[72:73], off offset:288
	s_waitcnt vmcnt(0)
	v_and_b32_e32 v59, 0xffff0000, v53
	v_lshlrev_b32_e32 v58, 16, v53
	v_and_b32_e32 v53, 0xffff0000, v52
	v_lshlrev_b32_e32 v52, 16, v52
	v_lshl_add_u64 v[54:55], v[140:141], 0, s[16:17]
	v_pk_add_f32 v[44:45], v[44:45], v[52:53]
	v_pk_add_f32 v[46:47], v[46:47], v[58:59]
	v_lshl_add_u64 v[56:57], v[54:55], 1, s[4:5]
	global_store_dwordx4 v[66:67], v[44:47], off offset:576 nt
	global_load_dwordx2 v[44:45], v[56:57], off
	v_lshl_add_u64 v[52:53], v[54:55], 2, s[48:49]
	s_waitcnt vmcnt(0)
	v_and_b32_e32 v47, 0xffff0000, v45
	v_lshlrev_b32_e32 v46, 16, v45
	v_and_b32_e32 v45, 0xffff0000, v44
	v_lshlrev_b32_e32 v44, 16, v44
	v_pk_add_f32 v[44:45], v[48:49], v[44:45]
	v_pk_add_f32 v[46:47], v[50:51], v[46:47]
	global_store_dwordx4 v[52:53], v[44:47], off nt
	global_load_dwordx2 v[44:45], v[56:57], off offset:32
	s_waitcnt vmcnt(0)
	v_and_b32_e32 v47, 0xffff0000, v45
	v_lshlrev_b32_e32 v46, 16, v45
	v_and_b32_e32 v45, 0xffff0000, v44
	v_lshlrev_b32_e32 v44, 16, v44
	v_pk_add_f32 v[40:41], v[40:41], v[44:45]
	v_pk_add_f32 v[42:43], v[42:43], v[46:47]
	global_store_dwordx4 v[52:53], v[40:43], off offset:64 nt
	global_load_dwordx2 v[40:41], v[56:57], off offset:256
	s_waitcnt vmcnt(0)
	v_and_b32_e32 v43, 0xffff0000, v41
	v_lshlrev_b32_e32 v42, 16, v41
	v_and_b32_e32 v41, 0xffff0000, v40
	v_lshlrev_b32_e32 v40, 16, v40
	v_pk_add_f32 v[36:37], v[36:37], v[40:41]
	v_pk_add_f32 v[38:39], v[38:39], v[42:43]
	global_store_dwordx4 v[52:53], v[36:39], off offset:512 nt
	global_load_dwordx2 v[36:37], v[56:57], off offset:288
	s_waitcnt vmcnt(0)
	v_and_b32_e32 v43, 0xffff0000, v37
	v_lshlrev_b32_e32 v42, 16, v37
	v_and_b32_e32 v37, 0xffff0000, v36
	v_lshlrev_b32_e32 v36, 16, v36
	v_lshl_add_u64 v[38:39], v[140:141], 0, s[18:19]
	v_pk_add_f32 v[28:29], v[28:29], v[36:37]
	v_pk_add_f32 v[30:31], v[30:31], v[42:43]
	v_lshl_add_u64 v[40:41], v[38:39], 1, s[4:5]
	global_store_dwordx4 v[52:53], v[28:31], off offset:576 nt
	global_load_dwordx2 v[28:29], v[40:41], off
	v_lshl_add_u64 v[36:37], v[38:39], 2, s[48:49]
	s_waitcnt vmcnt(0)
	v_and_b32_e32 v31, 0xffff0000, v29
	v_lshlrev_b32_e32 v30, 16, v29
	v_and_b32_e32 v29, 0xffff0000, v28
	v_lshlrev_b32_e32 v28, 16, v28
	v_pk_add_f32 v[28:29], v[32:33], v[28:29]
	v_pk_add_f32 v[30:31], v[34:35], v[30:31]
	global_store_dwordx4 v[36:37], v[28:31], off nt
	global_load_dwordx2 v[28:29], v[40:41], off offset:32
	s_waitcnt vmcnt(0)
	v_and_b32_e32 v31, 0xffff0000, v29
	v_lshlrev_b32_e32 v30, 16, v29
	v_and_b32_e32 v29, 0xffff0000, v28
	v_lshlrev_b32_e32 v28, 16, v28
	v_pk_add_f32 v[24:25], v[24:25], v[28:29]
	v_pk_add_f32 v[26:27], v[26:27], v[30:31]
	global_store_dwordx4 v[36:37], v[24:27], off offset:64 nt
	global_load_dwordx2 v[24:25], v[40:41], off offset:256
	s_waitcnt vmcnt(0)
	v_and_b32_e32 v27, 0xffff0000, v25
	v_lshlrev_b32_e32 v26, 16, v25
	v_and_b32_e32 v25, 0xffff0000, v24
	v_lshlrev_b32_e32 v24, 16, v24
	v_pk_add_f32 v[20:21], v[20:21], v[24:25]
	v_pk_add_f32 v[22:23], v[22:23], v[26:27]
	global_store_dwordx4 v[36:37], v[20:23], off offset:512 nt
	global_load_dwordx2 v[20:21], v[40:41], off offset:288
	s_waitcnt vmcnt(0)
	v_and_b32_e32 v27, 0xffff0000, v21
	v_lshlrev_b32_e32 v26, 16, v21
	v_and_b32_e32 v21, 0xffff0000, v20
	v_lshlrev_b32_e32 v20, 16, v20
	v_lshl_add_u64 v[22:23], v[140:141], 0, s[20:21]
	v_pk_add_f32 v[12:13], v[12:13], v[20:21]
	v_pk_add_f32 v[14:15], v[14:15], v[26:27]
	v_lshl_add_u64 v[24:25], v[22:23], 1, s[4:5]
	global_store_dwordx4 v[36:37], v[12:15], off offset:576 nt
	global_load_dwordx2 v[12:13], v[24:25], off
	v_lshl_add_u64 v[20:21], v[22:23], 2, s[48:49]
	s_waitcnt vmcnt(0)
	v_and_b32_e32 v15, 0xffff0000, v13
	v_lshlrev_b32_e32 v14, 16, v13
	v_and_b32_e32 v13, 0xffff0000, v12
	v_lshlrev_b32_e32 v12, 16, v12
	v_pk_add_f32 v[12:13], v[16:17], v[12:13]
	v_pk_add_f32 v[14:15], v[18:19], v[14:15]
	global_store_dwordx4 v[20:21], v[12:15], off nt
	global_load_dwordx2 v[12:13], v[24:25], off offset:32
	s_waitcnt vmcnt(0)
	v_and_b32_e32 v15, 0xffff0000, v13
	v_lshlrev_b32_e32 v14, 16, v13
	v_and_b32_e32 v13, 0xffff0000, v12
	v_lshlrev_b32_e32 v12, 16, v12
	v_pk_add_f32 v[8:9], v[8:9], v[12:13]
	v_pk_add_f32 v[10:11], v[10:11], v[14:15]
	global_store_dwordx4 v[20:21], v[8:11], off offset:64 nt
	global_load_dwordx2 v[8:9], v[24:25], off offset:256
	s_waitcnt vmcnt(0)
	v_and_b32_e32 v11, 0xffff0000, v9
	v_lshlrev_b32_e32 v10, 16, v9
	v_and_b32_e32 v9, 0xffff0000, v8
	v_lshlrev_b32_e32 v8, 16, v8
	v_pk_add_f32 v[4:5], v[4:5], v[8:9]
	v_pk_add_f32 v[6:7], v[6:7], v[10:11]
	global_store_dwordx4 v[20:21], v[4:7], off offset:512 nt
	global_load_dwordx2 v[4:5], v[24:25], off offset:288
	s_waitcnt vmcnt(0)
	v_and_b32_e32 v7, 0xffff0000, v5
	v_lshlrev_b32_e32 v6, 16, v5
	v_and_b32_e32 v5, 0xffff0000, v4
	v_lshlrev_b32_e32 v4, 16, v4
	v_pk_add_f32 v[0:1], v[0:1], v[4:5]
	v_pk_add_f32 v[2:3], v[2:3], v[6:7]
	global_store_dwordx4 v[20:21], v[0:3], off offset:576 nt
	s_cbranch_vccz .LBB0_1471
	s_waitcnt vmcnt(0)
	s_cmpk_gt_u32 s30, 0xff
	s_cbranch_scc1 .LBB0_1482
	s_barrier
